# v81 + exact counted vmcnt(3)/(2) for the K staging writes in the attention loop tail (waits at first consumer)
# baseline (speedup 1.0000x reference)
.LfixB_skip_h0:
	v_sub_u32_e32 v235, v248, v235
	v_sub_u32_e32 v234, v249, v234
	s_andn2_b64 vcc, exec, s[54:55]
	s_cbranch_vccnz .Lan_343_h0
	v_add_u32_e32 v255, v250, v235
	s_waitcnt vmcnt(3)
	ds_write_b128 v255, v[128:131]
	s_waitcnt vmcnt(2)
	ds_write_b128 v255, v[132:135] offset:8704
